# P0: x->bf16 conversion loop unrolled 4x with all 8 loads in flight and counted vmcnt (waitcnt placement lever)
# speedup vs baseline: 1.0026x; 1.0001x over previous
; __device__ __forceinline__ unsigned cvt_pk_bf16(float lo, float hi) { unsigned r; asm volatile("v_cvt_pk_bf16_f32 %0, %1, %2" : "=v"(r) : "v"(lo), "v"(hi)); return r; }
; __device__ __forceinline__ void p0_prologue(const Ptrs& P, unsigned char* lds, int tid, int G) {
;     ...
; #pragma unroll 4
;     for (size_t i = gt; i < (size_t)M * D / 8; i += GT) { const f32x4 a = *(const f32x4*)(P.x + i * 8), b = *(const f32x4*)(P.x + i * 8 + 4);
;         u32x4 w; w.x = cvt_pk_bf16(a[0], a[1]); w.y = cvt_pk_bf16(a[2], a[3]); w.z = cvt_pk_bf16(b[0], b[1]); w.w = cvt_pk_bf16(b[2], b[3]); *(u32x4*)(P.XB + i * 8) = w; }
.LBB0_101:
	s_or_b64 exec, exec, s[6:7]
	s_mov_b64 s[6:7], 0x800000
	v_cmp_gt_u64_e32 vcc, s[6:7], v[2:3]
	s_and_saveexec_b64 s[6:7], vcc
	s_cbranch_execz .LBB0_104
	s_lshl_b64 s[8:9], s[2:3], 14
	s_add_u32 s8, s36, s8
	v_mov_b32_e32 v7, 0
	s_addc_u32 s9, s37, s9
	v_lshl_add_u64 v[8:9], s[8:9], 0, v[6:7]
	s_lshl_b64 s[8:9], s[34:35], 14
	s_lshl_b64 s[10:11], s[2:3], 13
	s_add_u32 s10, s54, s10
	v_mov_b32_e32 v5, v7
	s_addc_u32 s11, s55, s11
	v_lshl_add_u64 v[8:9], v[8:9], 0, 16
	v_lshl_add_u64 v[4:5], s[10:11], 0, v[4:5]
	s_lshl_b64 s[10:11], s[34:35], 13
	s_mov_b64 s[12:13], 0
	s_mov_b64 s[14:15], 0x7fffff
	v_mov_b64_e32 v[6:7], v[2:3]
	s_lshl_b64 s[86:87], s[0:1], 1
	s_add_u32 s86, s86, s0
	s_addc_u32 s87, s87, s1
	s_lshl_b64 s[88:89], s[8:9], 2
	s_lshl_b64 s[90:91], s[10:11], 2
	s_lshl_b64 s[92:93], s[0:1], 2
.Lx4_loop:
	v_lshl_add_u64 v[18:19], v[6:7], 0, s[86:87]
	v_cmp_ge_u64_e32 vcc, s[14:15], v[18:19]
	s_and_b64 s[94:95], vcc, exec
	s_cmp_eq_u64 s[94:95], exec
	s_cbranch_scc0 .LBB0_103
	v_lshl_add_u64 v[52:53], v[8:9], 0, s[8:9]
	v_lshl_add_u64 v[54:55], v[52:53], 0, s[8:9]
	v_lshl_add_u64 v[56:57], v[54:55], 0, s[8:9]
	global_load_dwordx4 v[20:23], v[8:9], off offset:-16
	global_load_dwordx4 v[24:27], v[8:9], off
	global_load_dwordx4 v[28:31], v[52:53], off offset:-16
	global_load_dwordx4 v[32:35], v[52:53], off
	global_load_dwordx4 v[36:39], v[54:55], off offset:-16
	global_load_dwordx4 v[40:43], v[54:55], off
	global_load_dwordx4 v[44:47], v[56:57], off offset:-16
	global_load_dwordx4 v[48:51], v[56:57], off
	v_lshl_add_u64 v[58:59], v[4:5], 0, s[10:11]
	v_lshl_add_u64 v[60:61], v[58:59], 0, s[10:11]
	v_lshl_add_u64 v[62:63], v[60:61], 0, s[10:11]
	v_lshl_add_u64 v[6:7], v[6:7], 0, s[92:93]
	v_lshl_add_u64 v[8:9], v[8:9], 0, s[88:89]
	s_waitcnt vmcnt(6)
	v_cvt_pk_bf16_f32 v64, v20, v21
	v_cvt_pk_bf16_f32 v65, v22, v23
	v_cvt_pk_bf16_f32 v66, v24, v25
	v_cvt_pk_bf16_f32 v67, v26, v27
	global_store_dwordx4 v[4:5], v[64:67], off
	s_waitcnt vmcnt(5)
	v_cvt_pk_bf16_f32 v68, v28, v29
	v_cvt_pk_bf16_f32 v69, v30, v31
	v_cvt_pk_bf16_f32 v70, v32, v33
	v_cvt_pk_bf16_f32 v71, v34, v35
	global_store_dwordx4 v[58:59], v[68:71], off
	s_waitcnt vmcnt(4)
	v_cvt_pk_bf16_f32 v72, v36, v37
	v_cvt_pk_bf16_f32 v73, v38, v39
	v_cvt_pk_bf16_f32 v74, v40, v41
	v_cvt_pk_bf16_f32 v75, v42, v43
	global_store_dwordx4 v[60:61], v[72:75], off
	s_waitcnt vmcnt(3)
	v_cvt_pk_bf16_f32 v76, v44, v45
	v_cvt_pk_bf16_f32 v77, v46, v47
	v_cvt_pk_bf16_f32 v78, v48, v49
	v_cvt_pk_bf16_f32 v79, v50, v51
	global_store_dwordx4 v[62:63], v[76:79], off
	v_lshl_add_u64 v[4:5], v[4:5], 0, s[90:91]
	v_cmp_lt_u64_e32 vcc, s[14:15], v[6:7]
	s_or_b64 s[12:13], vcc, s[12:13]
	s_andn2_b64 exec, exec, s[12:13]
	s_cbranch_execnz .Lx4_loop
	s_branch .LBB0_104
	s_nop 0
